# accumulator clearing before each GEMM tile uses 64 v_mov_b64 of constant 0 instead of 127 single-register copies (P1, P7, P8, P10)
# speedup vs baseline: 1.0105x; 1.0105x over previous
.LBB0_169:
	s_ashr_i32 s51, s50, 31
	s_lshl_b64 s[12:13], s[50:51], 19
	s_add_u32 s52, s17, s12
	s_addc_u32 s53, s60, s13
	s_and_b64 s[12:13], s[40:41], exec
	s_cselect_b32 s3, s53, s9
	s_cselect_b32 s24, s52, s8
	s_ashr_i32 s49, s48, 31
	s_lshl_b64 s[12:13], s[48:49], 19
	s_add_u32 s54, s82, s12
	s_addc_u32 s55, s83, s13
	s_and_b64 s[12:13], s[40:41], exec
	s_cselect_b32 s25, s55, s11
	s_cselect_b32 s26, s54, s10
	s_add_u32 s8, s8, 0x40080
	s_addc_u32 s9, s9, 0
	s_add_u32 s27, s10, 0x100
	v_mov_b32_e32 v2, 0
	s_addc_u32 s28, s11, 0
	s_mov_b32 s29, -2
	v_mov_b64_e32 v[2:3], 0
	v_mov_b64_e32 v[4:5], 0
	v_mov_b64_e32 v[6:7], 0
	v_mov_b64_e32 v[8:9], 0
	v_mov_b64_e32 v[10:11], 0
	v_mov_b64_e32 v[12:13], 0
	v_mov_b64_e32 v[14:15], 0
	v_mov_b64_e32 v[16:17], 0
	v_mov_b64_e32 v[18:19], 0
	v_mov_b64_e32 v[20:21], 0
	v_mov_b64_e32 v[22:23], 0
	v_mov_b64_e32 v[24:25], 0
	v_mov_b64_e32 v[26:27], 0
	v_mov_b64_e32 v[28:29], 0
	v_mov_b64_e32 v[30:31], 0
	v_mov_b64_e32 v[32:33], 0
	v_mov_b64_e32 v[34:35], 0
	v_mov_b64_e32 v[36:37], 0
	v_mov_b64_e32 v[38:39], 0
	v_mov_b64_e32 v[40:41], 0
	v_mov_b64_e32 v[42:43], 0
	v_mov_b64_e32 v[44:45], 0
	v_mov_b64_e32 v[46:47], 0
	v_mov_b64_e32 v[48:49], 0
	v_mov_b64_e32 v[50:51], 0
	v_mov_b64_e32 v[52:53], 0
	v_mov_b64_e32 v[54:55], 0
	v_mov_b64_e32 v[56:57], 0
	v_mov_b64_e32 v[58:59], 0
	v_mov_b64_e32 v[60:61], 0
	v_mov_b64_e32 v[62:63], 0
	v_mov_b64_e32 v[64:65], 0
	v_mov_b64_e32 v[66:67], 0
	v_mov_b64_e32 v[68:69], 0
	v_mov_b64_e32 v[70:71], 0
	v_mov_b64_e32 v[72:73], 0
	v_mov_b64_e32 v[74:75], 0
	v_mov_b64_e32 v[76:77], 0
	v_mov_b64_e32 v[78:79], 0
	v_mov_b64_e32 v[80:81], 0
	v_mov_b64_e32 v[82:83], 0
	v_mov_b64_e32 v[84:85], 0
	v_mov_b64_e32 v[86:87], 0
	v_mov_b64_e32 v[88:89], 0
	v_mov_b64_e32 v[90:91], 0
	v_mov_b64_e32 v[92:93], 0
	v_mov_b64_e32 v[94:95], 0
	v_mov_b64_e32 v[96:97], 0
	v_mov_b64_e32 v[98:99], 0
	v_mov_b64_e32 v[100:101], 0
	v_mov_b64_e32 v[102:103], 0
	v_mov_b64_e32 v[104:105], 0
	v_mov_b64_e32 v[106:107], 0
	v_mov_b64_e32 v[108:109], 0
	v_mov_b64_e32 v[110:111], 0
	v_mov_b64_e32 v[112:113], 0
	v_mov_b64_e32 v[114:115], 0
	v_mov_b64_e32 v[116:117], 0
	v_mov_b64_e32 v[118:119], 0
	v_mov_b64_e32 v[120:121], 0
	v_mov_b64_e32 v[122:123], 0
	v_mov_b64_e32 v[124:125], 0
	v_mov_b64_e32 v[126:127], 0
	v_mov_b64_e32 v[128:129], 0

.LBB0_639:
	s_ashr_i32 s49, s48, 31
	s_lshl_b64 s[14:15], s[48:49], 19
	v_readlane_b32 s11, v254, 16
	s_add_u32 s50, s11, s14
	v_readlane_b32 s11, v254, 17
	s_addc_u32 s51, s11, s15
	s_and_b64 s[14:15], s[42:43], exec
	s_cselect_b32 s11, s51, s13
	s_cselect_b32 s14, s50, s12
	s_ashr_i32 s47, s46, 31
	s_lshl_b64 s[24:25], s[46:47], 19
	s_add_u32 s52, s74, s24
	s_addc_u32 s53, s75, s25
	s_and_b64 s[24:25], s[42:43], exec
	s_cselect_b32 s15, s53, s55
	s_cselect_b32 s24, s52, s54
	s_add_u32 s12, s12, 0x40080
	s_addc_u32 s13, s13, 0
	s_add_u32 s25, s54, 0x100
	v_mov_b32_e32 v0, 0
	s_addc_u32 s26, s55, 0
	s_mov_b32 s27, -2
	s_waitcnt lgkmcnt(0)
	v_mov_b64_e32 v[0:1], 0
	v_mov_b64_e32 v[2:3], 0
	v_mov_b64_e32 v[4:5], 0
	v_mov_b64_e32 v[6:7], 0
	v_mov_b64_e32 v[8:9], 0
	v_mov_b64_e32 v[10:11], 0
	v_mov_b64_e32 v[12:13], 0
	v_mov_b64_e32 v[14:15], 0
	v_mov_b64_e32 v[16:17], 0
	v_mov_b64_e32 v[18:19], 0
	v_mov_b64_e32 v[20:21], 0
	v_mov_b64_e32 v[22:23], 0
	v_mov_b64_e32 v[24:25], 0
	v_mov_b64_e32 v[26:27], 0
	v_mov_b64_e32 v[28:29], 0
	v_mov_b64_e32 v[30:31], 0
	v_mov_b64_e32 v[32:33], 0
	v_mov_b64_e32 v[34:35], 0
	v_mov_b64_e32 v[36:37], 0
	v_mov_b64_e32 v[38:39], 0
	v_mov_b64_e32 v[40:41], 0
	v_mov_b64_e32 v[42:43], 0
	v_mov_b64_e32 v[44:45], 0
	v_mov_b64_e32 v[46:47], 0
	v_mov_b64_e32 v[48:49], 0
	v_mov_b64_e32 v[50:51], 0
	v_mov_b64_e32 v[52:53], 0
	v_mov_b64_e32 v[54:55], 0
	v_mov_b64_e32 v[56:57], 0
	v_mov_b64_e32 v[58:59], 0
	v_mov_b64_e32 v[60:61], 0
	v_mov_b64_e32 v[62:63], 0
	v_mov_b64_e32 v[64:65], 0
	v_mov_b64_e32 v[66:67], 0
	v_mov_b64_e32 v[68:69], 0
	v_mov_b64_e32 v[70:71], 0
	v_mov_b64_e32 v[72:73], 0
	v_mov_b64_e32 v[74:75], 0
	v_mov_b64_e32 v[76:77], 0
	v_mov_b64_e32 v[78:79], 0
	v_mov_b64_e32 v[80:81], 0
	v_mov_b64_e32 v[82:83], 0
	v_mov_b64_e32 v[84:85], 0
	v_mov_b64_e32 v[86:87], 0
	v_mov_b64_e32 v[88:89], 0
	v_mov_b64_e32 v[90:91], 0
	v_mov_b64_e32 v[92:93], 0
	v_mov_b64_e32 v[94:95], 0
	v_mov_b64_e32 v[96:97], 0
	v_mov_b64_e32 v[98:99], 0
	v_mov_b64_e32 v[100:101], 0
	v_mov_b64_e32 v[102:103], 0
	v_mov_b64_e32 v[104:105], 0
	v_mov_b64_e32 v[106:107], 0
	v_mov_b64_e32 v[108:109], 0
	v_mov_b64_e32 v[110:111], 0
	v_mov_b64_e32 v[112:113], 0
	v_mov_b64_e32 v[114:115], 0
	v_mov_b64_e32 v[116:117], 0
	v_mov_b64_e32 v[118:119], 0
	v_mov_b64_e32 v[120:121], 0
	v_mov_b64_e32 v[122:123], 0
	v_mov_b64_e32 v[124:125], 0
	v_mov_b64_e32 v[126:127], 0

.LBB0_743:
	s_ashr_i32 s81, s80, 31
	s_lshl_b64 s[14:15], s[80:81], 19
	s_add_u32 s82, s96, s14
	s_addc_u32 s83, s97, s15
	s_and_b64 s[14:15], s[44:45], exec
	s_cselect_b32 s11, s83, s47
	s_cselect_b32 s14, s82, s46
	s_ashr_i32 s75, s74, 31
	s_lshl_b64 s[16:17], s[74:75], 19
	v_readlane_b32 s24, v254, 6
	v_readlane_b32 s25, v254, 7
	s_add_u32 s84, s24, s16
	s_addc_u32 s85, s25, s17
	s_and_b64 s[16:17], s[44:45], exec
	s_cselect_b32 s15, s85, s49
	s_cselect_b32 s16, s84, s48
	s_add_u32 s46, s46, 0x40080
	s_addc_u32 s47, s47, 0
	s_add_u32 s17, s48, 0x100
	v_mov_b32_e32 v64, 0
	s_addc_u32 s24, s49, 0
	s_mov_b32 s25, -2
	v_mov_b64_e32 v[0:1], 0
	v_mov_b64_e32 v[2:3], 0
	v_mov_b64_e32 v[4:5], 0
	v_mov_b64_e32 v[6:7], 0
	v_mov_b64_e32 v[8:9], 0
	v_mov_b64_e32 v[10:11], 0
	v_mov_b64_e32 v[12:13], 0
	v_mov_b64_e32 v[14:15], 0
	v_mov_b64_e32 v[16:17], 0
	v_mov_b64_e32 v[18:19], 0
	v_mov_b64_e32 v[20:21], 0
	v_mov_b64_e32 v[22:23], 0
	v_mov_b64_e32 v[24:25], 0
	v_mov_b64_e32 v[26:27], 0
	v_mov_b64_e32 v[28:29], 0
	v_mov_b64_e32 v[30:31], 0
	v_mov_b64_e32 v[32:33], 0
	v_mov_b64_e32 v[34:35], 0
	v_mov_b64_e32 v[36:37], 0
	v_mov_b64_e32 v[38:39], 0
	v_mov_b64_e32 v[40:41], 0
	v_mov_b64_e32 v[42:43], 0
	v_mov_b64_e32 v[44:45], 0
	v_mov_b64_e32 v[46:47], 0
	v_mov_b64_e32 v[48:49], 0
	v_mov_b64_e32 v[50:51], 0
	v_mov_b64_e32 v[52:53], 0
	v_mov_b64_e32 v[54:55], 0
	v_mov_b64_e32 v[56:57], 0
	v_mov_b64_e32 v[58:59], 0
	v_mov_b64_e32 v[60:61], 0
	v_mov_b64_e32 v[62:63], 0
	v_mov_b64_e32 v[64:65], 0
	v_mov_b64_e32 v[66:67], 0
	v_mov_b64_e32 v[68:69], 0
	v_mov_b64_e32 v[70:71], 0
	v_mov_b64_e32 v[72:73], 0
	v_mov_b64_e32 v[74:75], 0
	v_mov_b64_e32 v[76:77], 0
	v_mov_b64_e32 v[78:79], 0
	v_mov_b64_e32 v[96:97], 0
	v_mov_b64_e32 v[98:99], 0
	v_mov_b64_e32 v[100:101], 0
	v_mov_b64_e32 v[102:103], 0
	v_mov_b64_e32 v[104:105], 0
	v_mov_b64_e32 v[106:107], 0
	v_mov_b64_e32 v[108:109], 0
	v_mov_b64_e32 v[110:111], 0
	v_mov_b64_e32 v[112:113], 0
	v_mov_b64_e32 v[114:115], 0
	v_mov_b64_e32 v[116:117], 0
	v_mov_b64_e32 v[118:119], 0
	v_mov_b64_e32 v[120:121], 0
	v_mov_b64_e32 v[122:123], 0
	v_mov_b64_e32 v[124:125], 0
	v_mov_b64_e32 v[126:127], 0
	v_mov_b64_e32 v[136:137], 0
	v_mov_b64_e32 v[138:139], 0
	v_mov_b64_e32 v[140:141], 0
	v_mov_b64_e32 v[142:143], 0
	v_mov_b64_e32 v[144:145], 0
	v_mov_b64_e32 v[146:147], 0
	v_mov_b64_e32 v[148:149], 0
	v_mov_b64_e32 v[150:151], 0

.LBB0_954:
	s_add_u32 s13, s46, 0x100
	v_mov_b32_e32 v0, 0
	s_addc_u32 s14, s47, 0
	s_mov_b32 s15, -2
	v_mov_b64_e32 v[0:1], 0
	v_mov_b64_e32 v[2:3], 0
	v_mov_b64_e32 v[4:5], 0
	v_mov_b64_e32 v[6:7], 0
	v_mov_b64_e32 v[8:9], 0
	v_mov_b64_e32 v[10:11], 0
	v_mov_b64_e32 v[12:13], 0
	v_mov_b64_e32 v[14:15], 0
	v_mov_b64_e32 v[16:17], 0
	v_mov_b64_e32 v[18:19], 0
	v_mov_b64_e32 v[20:21], 0
	v_mov_b64_e32 v[22:23], 0
	v_mov_b64_e32 v[24:25], 0
	v_mov_b64_e32 v[26:27], 0
	v_mov_b64_e32 v[28:29], 0
	v_mov_b64_e32 v[30:31], 0
	v_mov_b64_e32 v[32:33], 0
	v_mov_b64_e32 v[34:35], 0
	v_mov_b64_e32 v[36:37], 0
	v_mov_b64_e32 v[38:39], 0
	v_mov_b64_e32 v[40:41], 0
	v_mov_b64_e32 v[42:43], 0
	v_mov_b64_e32 v[44:45], 0
	v_mov_b64_e32 v[46:47], 0
	v_mov_b64_e32 v[48:49], 0
	v_mov_b64_e32 v[50:51], 0
	v_mov_b64_e32 v[52:53], 0
	v_mov_b64_e32 v[54:55], 0
	v_mov_b64_e32 v[56:57], 0
	v_mov_b64_e32 v[58:59], 0
	v_mov_b64_e32 v[60:61], 0
	v_mov_b64_e32 v[62:63], 0
	v_mov_b64_e32 v[64:65], 0
	v_mov_b64_e32 v[66:67], 0
	v_mov_b64_e32 v[68:69], 0
	v_mov_b64_e32 v[70:71], 0
	v_mov_b64_e32 v[72:73], 0
	v_mov_b64_e32 v[74:75], 0
	v_mov_b64_e32 v[76:77], 0
	v_mov_b64_e32 v[78:79], 0
	v_mov_b64_e32 v[80:81], 0
	v_mov_b64_e32 v[82:83], 0
	v_mov_b64_e32 v[84:85], 0
	v_mov_b64_e32 v[86:87], 0
	v_mov_b64_e32 v[88:89], 0
	v_mov_b64_e32 v[90:91], 0
	v_mov_b64_e32 v[92:93], 0
	v_mov_b64_e32 v[94:95], 0
	v_mov_b64_e32 v[96:97], 0
	v_mov_b64_e32 v[98:99], 0
	v_mov_b64_e32 v[100:101], 0
	v_mov_b64_e32 v[102:103], 0
	v_mov_b64_e32 v[104:105], 0
	v_mov_b64_e32 v[106:107], 0
	v_mov_b64_e32 v[108:109], 0
	v_mov_b64_e32 v[110:111], 0
	v_mov_b64_e32 v[112:113], 0
	v_mov_b64_e32 v[114:115], 0
	v_mov_b64_e32 v[116:117], 0
	v_mov_b64_e32 v[118:119], 0
	v_mov_b64_e32 v[120:121], 0
	v_mov_b64_e32 v[122:123], 0
	v_mov_b64_e32 v[124:125], 0
	v_mov_b64_e32 v[126:127], 0
